# stack19: one-time barrier census issues its 16 counter loads back to back with a single wait (on top of stack18)
# baseline (speedup 1.0000x reference)
; __device__ __forceinline__ unsigned xb_ld(unsigned* p)              { return __hip_atomic_load(p, __ATOMIC_RELAXED, __HIP_MEMORY_SCOPE_AGENT); }
; __device__ __forceinline__ void xcd_barrier_complete(unsigned* bar, unsigned x, unsigned& nloc, unsigned& nx) {
;     ...
;     for (;;) {
;         sum = 0u; cnt = 0u; mine = 0u;
; #pragma unroll
;         for (unsigned j = 0; j < 16; ++j) { const unsigned c = xb_ld(&bar[XB_XCNT(j)]); sum += c; cnt += (c > 0u) ? 1u : 0u; mine = (j == x) ? c : mine; }
;         if (sum == G) break;
;         __builtin_amdgcn_s_sleep(1);
;         if ((++sp & 255u) == 0u) { if (xb_ld(&bar[XB_TMO])) break; if (sp > XB_SPIN_CAP) { atomicAdd(&bar[XB_TMO], 1u); break; } }
;     }
.LBB0_132:
	v_readlane_b32 s4, v242, 6
	v_readlane_b32 s5, v242, 7
	s_mov_b64 s[40:41], -1
	s_mov_b64 s[42:43], -1
	s_nop 4
	global_load_dword v0, v1, s[4:5] sc1
	v_readlane_b32 s4, v242, 8
	v_readlane_b32 s5, v242, 9
	s_waitcnt lgkmcnt(0)
	s_nop 3
	global_load_dword v2, v1, s[4:5] sc1
	v_readlane_b32 s4, v242, 10
	v_readlane_b32 s5, v242, 11
	s_nop 4
	global_load_dword v3, v1, s[4:5] sc1
	v_readlane_b32 s4, v242, 12
	v_readlane_b32 s5, v242, 13
	s_nop 4
	global_load_dword v4, v1, s[4:5] sc1
	v_readlane_b32 s4, v242, 14
	v_readlane_b32 s5, v242, 15
	s_nop 4
	global_load_dword v5, v1, s[4:5] sc1
	v_readlane_b32 s4, v242, 16
	v_readlane_b32 s5, v242, 17
	s_nop 4
	global_load_dword v6, v1, s[4:5] sc1
	v_readlane_b32 s4, v242, 18
	v_readlane_b32 s5, v242, 19
	s_nop 4
	global_load_dword v7, v1, s[4:5] sc1
	v_readlane_b32 s4, v242, 20
	v_readlane_b32 s5, v242, 21
	s_nop 4
	global_load_dword v8, v1, s[4:5] sc1
	v_readlane_b32 s4, v242, 22
	v_readlane_b32 s5, v242, 23
	s_nop 4
	global_load_dword v9, v1, s[4:5] sc1
	v_readlane_b32 s4, v242, 24
	v_readlane_b32 s5, v242, 25
	s_nop 4
	global_load_dword v10, v1, s[4:5] sc1
	v_readlane_b32 s4, v242, 26
	v_readlane_b32 s5, v242, 27
	s_nop 4
	global_load_dword v11, v1, s[4:5] sc1
	v_readlane_b32 s4, v242, 28
	v_readlane_b32 s5, v242, 29
	s_nop 4
	global_load_dword v12, v1, s[4:5] sc1
	v_readlane_b32 s4, v242, 30
	v_readlane_b32 s5, v242, 31
	s_nop 4
	global_load_dword v13, v1, s[4:5] sc1
	v_readlane_b32 s4, v242, 32
	v_readlane_b32 s5, v242, 33
	s_nop 4
	global_load_dword v14, v1, s[4:5] sc1
	v_readlane_b32 s4, v242, 34
	v_readlane_b32 s5, v242, 35
	s_nop 4
	global_load_dword v15, v1, s[4:5] sc1
	v_readlane_b32 s4, v242, 36
	v_readlane_b32 s5, v242, 37
	s_nop 4
	global_load_dword v16, v1, s[4:5] sc1
	v_readlane_b32 s4, v240, 51
	s_waitcnt vmcnt(0)
	v_add_u32_e32 v17, v2, v0
	v_add_u32_e32 v17, v17, v3
	v_add_u32_e32 v17, v17, v4
	v_add_u32_e32 v17, v17, v5
	v_add_u32_e32 v17, v17, v6
	v_add_u32_e32 v17, v17, v7
	v_add_u32_e32 v17, v17, v8
	v_add_u32_e32 v17, v17, v9
	v_add_u32_e32 v17, v17, v10
	v_add_u32_e32 v17, v17, v11
	v_add_u32_e32 v17, v17, v12
	v_add_u32_e32 v17, v17, v13
	v_add_u32_e32 v17, v17, v14
	v_add_u32_e32 v17, v17, v15
	v_add_u32_e32 v17, v17, v16
	v_cmp_eq_u32_e32 vcc, s4, v17
	s_cbranch_vccnz .LBB0_131
	s_and_b32 s4, s2, 0xff
	s_cmp_eq_u32 s4, 0
	s_mov_b64 s[44:45], -1
	s_sleep 1
	s_cbranch_scc1 .LBB0_136
	s_and_b64 vcc, exec, s[44:45]
	s_cbranch_vccz .LBB0_131
